# attention: LDS-DMA issue for tile t+3 moved behind the QK MFMAs (on top of K-fragment prefetch)
# baseline (speedup 1.0000x reference)
.LBB0_740:
	s_add_i32 s26, s48, 3
	s_cmp_ge_u32 s26, s46
	s_cselect_b64 s[2:3], -1, 0
.LBB0_743:
	s_sub_i32 s26, s49, 63
	s_cmp_le_i32 s26, s47
	s_cselect_b64 s[28:29], -1, 0
	s_cmp_gt_i32 s26, s47
	s_cbranch_scc1 .LBB0_756
	s_and_b32 s26, s48, 3
	s_mulk_i32 s26, 0x5800
	s_add_i32 s26, s26, 0
	v_add3_u32 v232, s26, v156, v146
	s_waitcnt lgkmcnt(0)
	v_mfma_f32_32x32x16_bf16 v[32:47], v[168:171], v[96:99], v[216:231]
	v_mfma_f32_32x32x16_bf16 v[48:63], v[192:195], v[96:99], v[216:231]
	ds_read_b128 v[108:111], v232 offset:13312
	ds_read_b128 v[124:127], v232 offset:17920
	v_mfma_f32_32x32x16_bf16 v[32:47], v[172:175], v[80:83], v[32:47]
	v_mfma_f32_32x32x16_bf16 v[48:63], v[196:199], v[80:83], v[48:63]
	ds_read_b128 v[104:107], v232 offset:13344
	ds_read_b128 v[120:123], v232 offset:17952
	v_mfma_f32_32x32x16_bf16 v[32:47], v[176:179], v[84:87], v[32:47]
	v_mfma_f32_32x32x16_bf16 v[48:63], v[200:203], v[84:87], v[48:63]
	ds_read_b128 v[112:115], v232 offset:13376
	ds_read_b128 v[132:135], v232 offset:17984
	v_mfma_f32_32x32x16_bf16 v[32:47], v[180:183], v[88:91], v[32:47]
	v_mfma_f32_32x32x16_bf16 v[48:63], v[204:207], v[88:91], v[48:63]
	ds_read_b128 v[116:119], v232 offset:13408
	ds_read_b128 v[128:131], v232 offset:18016
	v_mfma_f32_32x32x16_bf16 v[32:47], v[184:187], v[92:95], v[32:47]
	v_mfma_f32_32x32x16_bf16 v[48:63], v[208:211], v[92:95], v[48:63]
	v_mfma_f32_32x32x16_bf16 v[32:47], v[188:191], v[100:103], v[32:47]
	v_mfma_f32_32x32x16_bf16 v[48:63], v[212:215], v[100:103], v[48:63]
	s_mov_b64 s[26:27], -1
	s_and_b64 vcc, exec, s[2:3]
	s_cbranch_vccnz .LBB0_757
